# wide weight conversion routine (dwordx4 loads, 32 KiB per wave in flight, no LDS transpose) for phase-1 split conversions: NSA_IN rest, NSA_OUT, RG_OUT, HG_IN (both halves); bit-identical weights
# speedup vs baseline: 1.0129x; 1.0049x over previous
; __device__ __forceinline__ void p0_split_tail(Frame& F, int my, int nconv) {
;     const int gw0 = F.gw, ngw0 = F.ngw; F.gw = my * NWAVES + F.wave; F.ngw = nconv * NWAVES;
;     int it0 = 0;
;     p0_transpose_matrix2(F, FIN(F, 15), DM, HG_NP, (bf16*)FW(F, WS_W_HG_IN), HG_NP / 32 - P_HG_SPLIT, [](int nb) { return (P_HG_SPLIT + nb) * 32; }, [](int nb) { return (P_HG_SPLIT + nb) * 32; }, it0, FIN(F, 1) + 2 * DM);
;     F.gw = gw0; F.ngw = ngw0;
; }
.LBB0_260:
	v_readlane_b32 s4, v254, 7
	v_readlane_b32 s5, v254, 8
	s_waitcnt vmcnt(0)
	s_barrier
	s_barrier
	v_readlane_b32 s62, v254, 7
	v_readlane_b32 s63, v254, 8
	s_nop 3
	s_load_dwordx2 s[44:45], s[62:63], 0x78
	s_load_dwordx2 s[52:53], s[62:63], 0x8
	s_waitcnt lgkmcnt(0)
	s_add_u32 s52, s52, 0x8000
	s_addc_u32 s53, s53, 0
	s_mov_b32 s46, 0x10000
	s_mov_b32 s47, 0
	s_add_u32 s48, s70, 0x15600000
	s_addc_u32 s49, s71, 0
	s_mov_b32 s50, 64
	s_mov_b32 s51, 0x10
	s_mov_b32 s54, 256
	s_mov_b32 s55, 0
	s_lshl_b32 s56, s33, 3
	s_add_i32 s56, s56, s90
	s_mov_b32 s32, 0
	s_branch .Lcva_run
.Lcv_ret0:
	s_mov_b64 s[0:1], 0
.LBB0_263:
	s_and_b64 vcc, exec, s[0:1]
	s_cbranch_vccz .LBB0_386
	s_lshl_b32 s1, s30, 3
	s_lshl_b32 s0, s31, 7
	s_add_i32 s1, s90, s1
	s_add_i32 s18, s1, s0
	v_readlane_b32 s2, v254, 7
	s_add_i32 s19, s18, 0xffffff80
	v_readlane_b32 s3, v254, 8
	s_addk_i32 s18, 0x380
	s_load_dwordx2 s[0:1], s[2:3], 0x8
	s_nop 0
	s_load_dwordx2 s[2:3], s[2:3], 0x18
	s_ashr_i32 s5, s18, 31
	s_lshr_b32 s5, s5, 22
	s_add_i32 s5, s18, s5
	v_and_b32_e32 v3, 7, v216
	v_mov_b32_e32 v2, 0
	s_lshl_b32 s4, s90, 14
	s_and_b32 s5, s5, 0xfffffc00
	v_lshlrev_b32_e32 v4, 5, v3
	v_mov_b32_e32 v5, v2
	v_and_b32_e32 v20, 31, v216
	s_add_i32 s4, s4, 0
	s_sub_i32 s20, s18, s5
	s_waitcnt lgkmcnt(0)
	v_lshl_add_u64 v[22:23], s[0:1], 0, v[4:5]
	v_lshrrev_b32_e32 v1, 5, v173
	v_lshlrev_b32_e32 v4, 2, v20
	s_cmp_lg_u64 s[0:1], 0
	v_lshl_add_u64 v[24:25], s[2:3], 0, v[4:5]
	v_mul_u32_u24_e32 v5, 0x84, v1
	v_lshrrev_b32_e32 v35, 3, v173
	s_cselect_b64 s[12:13], -1, 0
	v_lshlrev_b32_e32 v18, 3, v3
	v_add3_u32 v34, s4, v5, v4
	v_mul_u32_u24_e32 v6, 0x420, v3
	v_lshlrev_b32_e32 v4, 4, v3
	v_mov_b32_e32 v5, v2
	v_lshlrev_b32_e32 v3, 2, v35
	s_mov_b32 s9, 0
	v_lshl_add_u64 v[4:5], s[70:71], 0, v[4:5]
	s_mov_b64 s[2:3], 0x200000
	v_add3_u32 v36, s4, v6, v3
	v_cndmask_b32_e64 v3, 0, 1, s[12:13]
	v_lshl_add_u64 v[26:27], v[4:5], 0, s[2:3]
	v_cmp_eq_u32_e64 s[4:5], 0, v216
	s_mov_b64 s[10:11], -1
	s_lshl_b32 s21, s20, 5
	v_cmp_ne_u32_e64 s[2:3], 1, v3
	s_mov_b32 s22, 0xb180
	v_add_u32_e32 v19, 0x400, v34
	v_add_u32_e32 v21, 0x800, v34
	v_add_u32_e32 v37, 0xc00, v34
	v_add_u32_e32 v38, 0x1000, v34
	v_add_u32_e32 v39, 0x1400, v34
	v_add_u32_e32 v40, 0x1800, v34
	v_add_u32_e32 v41, 0x1c00, v34
	v_mov_b32_e32 v3, v2
	v_mov_b32_e32 v4, v2
	v_mov_b32_e32 v5, v2
	s_mov_b32 s12, s9
	s_branch .LBB0_266

; __device__ __forceinline__ unsigned pk2(float lo, float hi) { unsigned r; asm volatile("v_cvt_pk_bf16_f32 %0, %1, %2" : "=v"(r) : "v"(lo), "v"(hi)); return r; }
; __device__ __forceinline__ void p0_transpose_item(const float* W, int K, int N, bf16* WT, int kb, int src_col0, int dst_row0, float* scr, int lane, const float* kgain = nullptr) {
;     const int k0 = 64 * kb, c = lane & 7;
;     v4f g0 = (v4f){1.f, 1.f, 1.f, 1.f}, g1 = g0;
;     if (src_col0 >= 0) {
;         float wv[32];
;         if (kgain) { g0 = *(const v4f*)(kgain + k0 + 8 * c); g1 = *(const v4f*)(kgain + k0 + 8 * c + 4); }
; #pragma unroll
;         for (int i = 0; i < 32; ++i) { const int kk = 2 * i + (lane >> 5); wv[i] = __builtin_nontemporal_load(&W[(size_t)(k0 + kk) * N + src_col0 + (lane & 31)]); }
; #pragma unroll
;         for (int i = 0; i < 32; ++i) { const int kk = 2 * i + (lane >> 5); scr[kk * 33 + (lane & 31)] = wv[i]; }
;     }
;     __builtin_amdgcn_s_waitcnt(0xC07F); asm volatile("" ::: "memory");
; #pragma unroll
;     for (int j = 0; j < 4; ++j) { const int n = (lane >> 3) + 8 * j; const float* s = scr + (8 * c) * 33 + n;
;         v4u o;
;         if (src_col0 >= 0) { o.x = pk2(s[0 * 33] * g0.x, s[1 * 33] * g0.y); o.y = pk2(s[2 * 33] * g0.z, s[3 * 33] * g0.w); o.z = pk2(s[4 * 33] * g1.x, s[5 * 33] * g1.y); o.w = pk2(s[6 * 33] * g1.z, s[7 * 33] * g1.w); }
;         else { o.x = 0u; o.y = 0u; o.z = 0u; o.w = 0u; }
;         *(v4u*)(WT + (size_t)(dst_row0 + n) * K + k0 + 8 * c) = o; }
; __device__ __forceinline__ void p0_split_convert(Frame& F, int my, int nconv, unsigned* flag) {
;     ...
;     p0_transpose_matrix2(F, FIN(F, 3), DM, 11360, (bf16*)FW(F, WS_W_NSA_IN), NSA_NP / 32 - 64, [=](int nb) { return cm(64 + nb); }, [=](int nb) { return (64 + nb) * 32; }, it0, FIN(F, 1) + 0 * DM);
;     p0_transpose_matrix(F, FIN(F, 7), DM, DM, (bf16*)FW(F, WS_W_NSA_OUT), DM / 32, [](int nb) { return nb * 32; }, it0);
;     p0_transpose_matrix(F, FIN(F, 14), DM, DM, (bf16*)FW(F, WS_W_RG_OUT), DM / 32, [](int nb) { return nb * 32; }, it0);
;     p0_transpose_matrix(F, FIN(F, 15), DM, HG_NP, (bf16*)FW(F, WS_W_HG_IN), P_HG_SPLIT, [](int nb) { return nb * 32; }, it0, FIN(F, 1) + 2 * DM);
.LBB0_285:
	v_readlane_b32 s62, v254, 7
	v_readlane_b32 s63, v254, 8
	s_nop 3
	s_load_dwordx2 s[44:45], s[62:63], 0x18
	s_load_dwordx2 s[52:53], s[62:63], 0x8
	s_waitcnt lgkmcnt(0)
	s_mov_b32 s46, 0xb180
	s_mov_b32 s47, 1
	s_add_u32 s48, s70, 0x200000
	s_addc_u32 s49, s71, 0
	s_mov_b32 s50, 74
	s_mov_b32 s51, 0x3e000d
	s_mov_b32 s54, 64
	s_mov_b32 s55, 0
	s_mov_b32 s56, s19
	s_mov_b32 s32, 1
	s_branch .Lcva_run
.Lcv_ret1:
	v_readlane_b32 s62, v254, 7
	v_readlane_b32 s63, v254, 8
	s_nop 3
	s_load_dwordx2 s[44:45], s[62:63], 0x38
	s_waitcnt lgkmcnt(0)
	s_mov_b64 s[52:53], 0
	s_mov_b32 s46, 0x4000
	s_mov_b32 s47, 0
	s_add_u32 s48, s70, 0xb600000
	s_addc_u32 s49, s71, 0
	s_mov_b32 s50, 32
	s_mov_b32 s51, 0x20
	s_mov_b32 s54, 0
	s_mov_b32 s55, 640
	s_mov_b32 s56, s19
	s_mov_b32 s32, 2
	s_branch .Lcva_run
.Lcv_ret2:
	v_readlane_b32 s62, v254, 7
	v_readlane_b32 s63, v254, 8
	s_nop 3
	s_load_dwordx2 s[44:45], s[62:63], 0x70
	s_waitcnt lgkmcnt(0)
	s_mov_b64 s[52:53], 0
	s_mov_b32 s46, 0x4000
	s_mov_b32 s47, 0
	s_add_u32 s48, s70, 0x13600000
	s_addc_u32 s49, s71, 0
	s_mov_b32 s50, 32
	s_mov_b32 s51, 0x20
	s_mov_b32 s54, 0
	s_mov_b32 s55, 640
	s_mov_b32 s56, s19
	s_mov_b32 s32, 3
	s_branch .Lcva_run
.Lcv_ret3:
	v_readlane_b32 s62, v254, 7
	v_readlane_b32 s63, v254, 8
	s_nop 3
	s_load_dwordx2 s[44:45], s[62:63], 0x78
	s_load_dwordx2 s[52:53], s[62:63], 0x8
	s_waitcnt lgkmcnt(0)
	s_add_u32 s52, s52, 0x8000
	s_addc_u32 s53, s53, 0
	s_mov_b32 s46, 0x10000
	s_mov_b32 s47, 0
	s_add_u32 s48, s70, 0x15600000
	s_addc_u32 s49, s71, 0
	s_mov_b32 s50, 64
	s_mov_b32 s51, 0x10
	s_mov_b32 s54, 0
	s_mov_b32 s55, 640
	s_mov_b32 s56, s19
	s_mov_b32 s32, 4
	s_branch .Lcva_run
.Lcv_ret4:
	v_and_b32_e32 v14, 31, v216
	v_lshlrev_b32_e32 v14, 2, v14
	v_and_b32_e32 v16, 7, v216
	v_lshlrev_b32_e32 v16, 4, v16
	s_branch .LBB0_343
.Lcva_run:
	v_and_b32_e32 v172, 63, v216
	v_lshlrev_b32_e32 v192, 4, v172
	v_lshrrev_b32_e32 v174, 3, v172
	v_and_b32_e32 v175, 7, v172
	s_lshl_b32 s64, s90, 14
	v_add_u32_e32 v193, s64, v192
	s_cmp_eq_u64 s[52:53], 0
	s_cbranch_scc1 .Lcva_nogain
	global_load_dwordx4 v[44:47], v192, s[52:53]
	global_load_dwordx4 v[48:51], v192, s[52:53] offset:1024
	global_load_dwordx4 v[52:55], v192, s[52:53] offset:2048
	global_load_dwordx4 v[56:59], v192, s[52:53] offset:3072
	s_add_u32 s52, s52, 0x1000
	s_addc_u32 s53, s53, 0
	global_load_dwordx4 v[60:63], v192, s[52:53]
	global_load_dwordx4 v[64:67], v192, s[52:53] offset:1024
	global_load_dwordx4 v[68:71], v192, s[52:53] offset:2048
	global_load_dwordx4 v[72:75], v192, s[52:53] offset:3072
	s_add_u32 s52, s52, 0x1000
	s_addc_u32 s53, s53, 0
	global_load_dwordx4 v[76:79], v192, s[52:53]
	global_load_dwordx4 v[80:83], v192, s[52:53] offset:1024
	global_load_dwordx4 v[84:87], v192, s[52:53] offset:2048
	global_load_dwordx4 v[88:91], v192, s[52:53] offset:3072
	s_add_u32 s52, s52, 0x1000
	s_addc_u32 s53, s53, 0
	global_load_dwordx4 v[92:95], v192, s[52:53]
	global_load_dwordx4 v[96:99], v192, s[52:53] offset:1024
	global_load_dwordx4 v[100:103], v192, s[52:53] offset:2048
	global_load_dwordx4 v[104:107], v192, s[52:53] offset:3072
	s_waitcnt vmcnt(0)
	ds_write_b128 v193, v[44:47]
	ds_write_b128 v193, v[48:51] offset:1024
	ds_write_b128 v193, v[52:55] offset:2048
	ds_write_b128 v193, v[56:59] offset:3072
	ds_write_b128 v193, v[60:63] offset:4096
	ds_write_b128 v193, v[64:67] offset:5120
	ds_write_b128 v193, v[68:71] offset:6144
	ds_write_b128 v193, v[72:75] offset:7168
	ds_write_b128 v193, v[76:79] offset:8192
	ds_write_b128 v193, v[80:83] offset:9216
	ds_write_b128 v193, v[84:87] offset:10240
	ds_write_b128 v193, v[88:91] offset:11264
	ds_write_b128 v193, v[92:95] offset:12288
	ds_write_b128 v193, v[96:99] offset:13312
	ds_write_b128 v193, v[100:103] offset:14336
	ds_write_b128 v193, v[104:107] offset:15360
	s_branch .Lcva_gdone
.Lcva_nogain:
	v_mov_b32_e32 v44, 1.0
	v_mov_b32_e32 v45, 1.0
	v_mov_b32_e32 v46, 1.0
	v_mov_b32_e32 v47, 1.0
	ds_write_b128 v193, v[44:47]
	ds_write_b128 v193, v[44:47] offset:1024
	ds_write_b128 v193, v[44:47] offset:2048
	ds_write_b128 v193, v[44:47] offset:3072
	ds_write_b128 v193, v[44:47] offset:4096
	ds_write_b128 v193, v[44:47] offset:5120
	ds_write_b128 v193, v[44:47] offset:6144
	ds_write_b128 v193, v[44:47] offset:7168
	ds_write_b128 v193, v[44:47] offset:8192
	ds_write_b128 v193, v[44:47] offset:9216
	ds_write_b128 v193, v[44:47] offset:10240
	ds_write_b128 v193, v[44:47] offset:11264
	ds_write_b128 v193, v[44:47] offset:12288
	ds_write_b128 v193, v[44:47] offset:13312
	ds_write_b128 v193, v[44:47] offset:14336
	ds_write_b128 v193, v[44:47] offset:15360
.Lcva_gdone:
	v_lshlrev_b32_e32 v194, 3, v174
	v_mul_lo_u32 v194, v194, s46
	v_lshl_add_u32 v172, v175, 4, v194
	v_lshlrev_b32_e32 v194, 15, v175
	v_lshl_add_u32 v195, v174, 5, s64
	v_lshl_add_u32 v174, v174, 4, v194
	v_mov_b32_e32 v175, v195
	s_sub_i32 s58, s56, s55
	s_and_b32 s55, s58, 0x3ff
	s_mov_b32 s61, 0
.Lcva_norm:
	s_cmp_lt_u32 s55, s50
	s_cbranch_scc1 .Lcva_normd
	s_sub_i32 s55, s55, s50
	s_add_i32 s61, s61, 1
	s_branch .Lcva_norm
.Lcva_normd:
	s_mov_b32 s59, 0
	s_mov_b32 s60, 2
	s_cmp_ge_u32 s61, 64
	s_cbranch_scc1 .Lcva_exit
	s_lshl_b32 vcc_lo, s55, 2
	s_add_i32 vcc_lo, vcc_lo, s54
	s_add_i32 vcc_lo, vcc_lo, 0
	s_lshl_b32 vcc_hi, vcc_lo, 7
	s_cmp_eq_u32 s47, 0
	s_cbranch_scc1 .Lcva_col_p0
	s_cmp_lt_u32 vcc_lo, 0xe0
	s_cbranch_scc1 .Lcva_col_p0
	s_add_i32 vcc_hi, vcc_hi, 0x180
	s_cmp_lt_u32 vcc_lo, 0x160
	s_cbranch_scc1 .Lcva_col_p0
	s_sub_i32 vcc_hi, vcc_hi, 0x4180
	s_cmp_lt_u32 vcc_lo, 0x163
	s_cbranch_scc1 .Lcva_col_p0
	s_mov_b32 vcc_hi, 0
	s_or_b32 s59, s59, 16
; __device__ __forceinline__ void p0_transpose_item(const float* W, int K, int N, bf16* WT, int kb, int src_col0, int dst_row0, float* scr, int lane, const float* kgain = nullptr) {
;     const int k0 = 64 * kb, c = lane & 7;
;     v4f g0 = (v4f){1.f, 1.f, 1.f, 1.f}, g1 = g0;
;     if (src_col0 >= 0) {
;         float wv[32];
;         if (kgain) { g0 = *(const v4f*)(kgain + k0 + 8 * c); g1 = *(const v4f*)(kgain + k0 + 8 * c + 4); }
; #pragma unroll
;         for (int i = 0; i < 32; ++i) { const int kk = 2 * i + (lane >> 5); wv[i] = __builtin_nontemporal_load(&W[(size_t)(k0 + kk) * N + src_col0 + (lane & 31)]); }
.Lcva_col_p0:
	s_lshl_b32 vcc_lo, s61, 6
	s_mul_i32 vcc_lo, vcc_lo, s46
	s_add_u32 s62, s44, vcc_lo
	s_addc_u32 s63, s45, 0
	s_add_u32 s62, s62, vcc_hi
	s_addc_u32 s63, s63, 0
	global_load_dwordx4 v[44:47], v172, s[62:63] nt
	s_add_u32 s62, s62, s46
	s_addc_u32 s63, s63, 0
	global_load_dwordx4 v[48:51], v172, s[62:63] nt
	s_add_u32 s62, s62, s46
	s_addc_u32 s63, s63, 0
	global_load_dwordx4 v[52:55], v172, s[62:63] nt
	s_add_u32 s62, s62, s46
	s_addc_u32 s63, s63, 0
	global_load_dwordx4 v[56:59], v172, s[62:63] nt
	s_add_u32 s62, s62, s46
	s_addc_u32 s63, s63, 0
	global_load_dwordx4 v[60:63], v172, s[62:63] nt
	s_add_u32 s62, s62, s46
	s_addc_u32 s63, s63, 0
	global_load_dwordx4 v[64:67], v172, s[62:63] nt
	s_add_u32 s62, s62, s46
	s_addc_u32 s63, s63, 0
	global_load_dwordx4 v[68:71], v172, s[62:63] nt
	s_add_u32 s62, s62, s46
	s_addc_u32 s63, s63, 0
	global_load_dwordx4 v[72:75], v172, s[62:63] nt
	s_lshl_b32 vcc_lo, s55, 2
	s_add_i32 vcc_lo, vcc_lo, s54
	s_add_i32 vcc_lo, vcc_lo, 1
	s_lshl_b32 vcc_hi, vcc_lo, 7
	s_cmp_eq_u32 s47, 0
	s_cbranch_scc1 .Lcva_col_p1
	s_cmp_lt_u32 vcc_lo, 0xe0
	s_cbranch_scc1 .Lcva_col_p1
	s_add_i32 vcc_hi, vcc_hi, 0x180
	s_cmp_lt_u32 vcc_lo, 0x160
	s_cbranch_scc1 .Lcva_col_p1
	s_sub_i32 vcc_hi, vcc_hi, 0x4180
	s_cmp_lt_u32 vcc_lo, 0x163
	s_cbranch_scc1 .Lcva_col_p1
	s_mov_b32 vcc_hi, 0
	s_or_b32 s59, s59, 32
.Lcva_col_p1:
	s_lshl_b32 vcc_lo, s61, 6
	s_mul_i32 vcc_lo, vcc_lo, s46
	s_add_u32 s62, s44, vcc_lo
	s_addc_u32 s63, s45, 0
	s_add_u32 s62, s62, vcc_hi
	s_addc_u32 s63, s63, 0
	global_load_dwordx4 v[76:79], v172, s[62:63] nt
	s_add_u32 s62, s62, s46
	s_addc_u32 s63, s63, 0
	global_load_dwordx4 v[80:83], v172, s[62:63] nt
	s_add_u32 s62, s62, s46
	s_addc_u32 s63, s63, 0
	global_load_dwordx4 v[84:87], v172, s[62:63] nt
	s_add_u32 s62, s62, s46
	s_addc_u32 s63, s63, 0
	global_load_dwordx4 v[88:91], v172, s[62:63] nt
	s_add_u32 s62, s62, s46
	s_addc_u32 s63, s63, 0
	global_load_dwordx4 v[92:95], v172, s[62:63] nt
	s_add_u32 s62, s62, s46
	s_addc_u32 s63, s63, 0
	global_load_dwordx4 v[96:99], v172, s[62:63] nt
	s_add_u32 s62, s62, s46
	s_addc_u32 s63, s63, 0
	global_load_dwordx4 v[100:103], v172, s[62:63] nt
	s_add_u32 s62, s62, s46
	s_addc_u32 s63, s63, 0
	global_load_dwordx4 v[104:107], v172, s[62:63] nt
	s_lshl_b32 vcc_lo, s55, 2
	s_add_i32 vcc_lo, vcc_lo, s54
	s_add_i32 vcc_lo, vcc_lo, 2
	s_lshl_b32 vcc_hi, vcc_lo, 7
	s_cmp_eq_u32 s47, 0
	s_cbranch_scc1 .Lcva_col_p2
	s_cmp_lt_u32 vcc_lo, 0xe0
	s_cbranch_scc1 .Lcva_col_p2
	s_add_i32 vcc_hi, vcc_hi, 0x180
	s_cmp_lt_u32 vcc_lo, 0x160
	s_cbranch_scc1 .Lcva_col_p2
	s_sub_i32 vcc_hi, vcc_hi, 0x4180
	s_cmp_lt_u32 vcc_lo, 0x163
	s_cbranch_scc1 .Lcva_col_p2
	s_mov_b32 vcc_hi, 0
	s_or_b32 s59, s59, 64
.Lcva_col_p2:
	s_lshl_b32 vcc_lo, s61, 6
	s_mul_i32 vcc_lo, vcc_lo, s46
	s_add_u32 s62, s44, vcc_lo
	s_addc_u32 s63, s45, 0
	s_add_u32 s62, s62, vcc_hi
	s_addc_u32 s63, s63, 0
	global_load_dwordx4 v[108:111], v172, s[62:63] nt
	s_add_u32 s62, s62, s46
	s_addc_u32 s63, s63, 0
	global_load_dwordx4 v[112:115], v172, s[62:63] nt
	s_add_u32 s62, s62, s46
	s_addc_u32 s63, s63, 0
	global_load_dwordx4 v[116:119], v172, s[62:63] nt
	s_add_u32 s62, s62, s46
	s_addc_u32 s63, s63, 0
	global_load_dwordx4 v[120:123], v172, s[62:63] nt
	s_add_u32 s62, s62, s46
	s_addc_u32 s63, s63, 0
	global_load_dwordx4 v[124:127], v172, s[62:63] nt
	s_add_u32 s62, s62, s46
	s_addc_u32 s63, s63, 0
	global_load_dwordx4 v[128:131], v172, s[62:63] nt
	s_add_u32 s62, s62, s46
	s_addc_u32 s63, s63, 0
	global_load_dwordx4 v[132:135], v172, s[62:63] nt
	s_add_u32 s62, s62, s46
	s_addc_u32 s63, s63, 0
	global_load_dwordx4 v[136:139], v172, s[62:63] nt
	s_lshl_b32 vcc_lo, s55, 2
	s_add_i32 vcc_lo, vcc_lo, s54
	s_add_i32 vcc_lo, vcc_lo, 3
	s_lshl_b32 vcc_hi, vcc_lo, 7
	s_cmp_eq_u32 s47, 0
	s_cbranch_scc1 .Lcva_col_p3
	s_cmp_lt_u32 vcc_lo, 0xe0
	s_cbranch_scc1 .Lcva_col_p3
	s_add_i32 vcc_hi, vcc_hi, 0x180
	s_cmp_lt_u32 vcc_lo, 0x160
	s_cbranch_scc1 .Lcva_col_p3
	s_sub_i32 vcc_hi, vcc_hi, 0x4180
	s_cmp_lt_u32 vcc_lo, 0x163
	s_cbranch_scc1 .Lcva_col_p3
	s_mov_b32 vcc_hi, 0
	s_or_b32 s59, s59, 128
.Lcva_col_p3:
	s_lshl_b32 vcc_lo, s61, 6
	s_mul_i32 vcc_lo, vcc_lo, s46
	s_add_u32 s62, s44, vcc_lo
	s_addc_u32 s63, s45, 0
	s_add_u32 s62, s62, vcc_hi
	s_addc_u32 s63, s63, 0
	global_load_dwordx4 v[140:143], v172, s[62:63] nt
	s_add_u32 s62, s62, s46
	s_addc_u32 s63, s63, 0
	global_load_dwordx4 v[144:147], v172, s[62:63] nt
	s_add_u32 s62, s62, s46
	s_addc_u32 s63, s63, 0
	global_load_dwordx4 v[148:151], v172, s[62:63] nt
	s_add_u32 s62, s62, s46
	s_addc_u32 s63, s63, 0
	global_load_dwordx4 v[152:155], v172, s[62:63] nt
	s_add_u32 s62, s62, s46
	s_addc_u32 s63, s63, 0
	global_load_dwordx4 v[156:159], v172, s[62:63] nt
	s_add_u32 s62, s62, s46
	s_addc_u32 s63, s63, 0
	global_load_dwordx4 v[160:163], v172, s[62:63] nt
	s_add_u32 s62, s62, s46
	s_addc_u32 s63, s63, 0
	global_load_dwordx4 v[164:167], v172, s[62:63] nt
	s_add_u32 s62, s62, s46
	s_addc_u32 s63, s63, 0
	global_load_dwordx4 v[168:171], v172, s[62:63] nt
.Lcva_loop:
	s_mov_b32 s57, s61
	s_mov_b32 s58, s55
	s_lshr_b32 s59, s59, 4
	s_bfe_u32 s64, s51, 0x100010
	s_and_b32 s43, s51, 0xffff
	s_add_i32 s55, s58, s64
	s_add_i32 s61, s57, s43
	s_cmp_ge_u32 s55, s50
	s_cbranch_scc0 .Lcva_nowrap
	s_sub_i32 s55, s55, s50
	s_add_i32 s61, s61, 1
.Lcva_nowrap:
	s_andn2_b32 s60, s60, 1
	s_cmp_lt_u32 s61, 64
	s_cbranch_scc0 .Lcva_nonext
	s_or_b32 s60, s60, 1
; __device__ __forceinline__ unsigned pk2(float lo, float hi) { unsigned r; asm volatile("v_cvt_pk_bf16_f32 %0, %1, %2" : "=v"(r) : "v"(lo), "v"(hi)); return r; }
; __device__ __forceinline__ void p0_transpose_item(const float* W, int K, int N, bf16* WT, int kb, int src_col0, int dst_row0, float* scr, int lane, const float* kgain = nullptr) {
;     ...
;     __builtin_amdgcn_s_waitcnt(0xC07F); asm volatile("" ::: "memory");
; #pragma unroll
;     for (int j = 0; j < 4; ++j) { const int n = (lane >> 3) + 8 * j; const float* s = scr + (8 * c) * 33 + n;
;         v4u o;
;         if (src_col0 >= 0) { o.x = pk2(s[0 * 33] * g0.x, s[1 * 33] * g0.y); o.y = pk2(s[2 * 33] * g0.z, s[3 * 33] * g0.w); o.z = pk2(s[4 * 33] * g1.x, s[5 * 33] * g1.y); o.w = pk2(s[6 * 33] * g1.z, s[7 * 33] * g1.w); }
;         else { o.x = 0u; o.y = 0u; o.z = 0u; o.w = 0u; }
;         *(v4u*)(WT + (size_t)(dst_row0 + n) * K + k0 + 8 * c) = o; }
;     __builtin_amdgcn_s_waitcnt(0xC07F); asm volatile("" ::: "memory");
.Lcva_nonext:
	s_lshl_b32 s64, s58, 2
	s_add_i32 s64, s64, s54
	s_lshl_b32 s64, s64, 18
	s_lshl_b32 s43, s57, 7
	s_add_i32 s64, s64, s43
	s_add_u32 s52, s48, s64
	s_addc_u32 s53, s49, 0
	s_lshl_b32 s43, s57, 8
	v_add_u32_e32 v193, s43, v175
	ds_read_b128 v[176:179], v193
	ds_read_b128 v[180:183], v193 offset:16
	s_bitcmp1_b32 s60, 0
	s_cbranch_scc0 .Lcva_wl_0
	s_bitcmp1_b32 s60, 1
	s_cbranch_scc1 .Lcva_wf_0
	s_waitcnt vmcnt(36)
	s_branch .Lcva_wd_0
.Lcva_wf_0:
	s_waitcnt vmcnt(24)
	s_branch .Lcva_wd_0
.Lcva_wl_0:
	s_waitcnt vmcnt(24)
.Lcva_wd_0:
	s_waitcnt lgkmcnt(0)
	s_bitcmp1_b32 s59, 0
	s_cbranch_scc1 .Lcva_pad_0
	v_mul_f32_e32 v44, v176, v44
	v_mul_f32_e32 v45, v176, v45
	v_mul_f32_e32 v46, v176, v46
	v_mul_f32_e32 v47, v176, v47
	v_mul_f32_e32 v48, v177, v48
	v_mul_f32_e32 v49, v177, v49
	v_mul_f32_e32 v50, v177, v50
	v_mul_f32_e32 v51, v177, v51
	v_mul_f32_e32 v52, v178, v52
	v_mul_f32_e32 v53, v178, v53
	v_mul_f32_e32 v54, v178, v54
	v_mul_f32_e32 v55, v178, v55
	v_mul_f32_e32 v56, v179, v56
	v_mul_f32_e32 v57, v179, v57
	v_mul_f32_e32 v58, v179, v58
	v_mul_f32_e32 v59, v179, v59
	v_mul_f32_e32 v60, v180, v60
	v_mul_f32_e32 v61, v180, v61
	v_mul_f32_e32 v62, v180, v62
	v_mul_f32_e32 v63, v180, v63
	v_mul_f32_e32 v64, v181, v64
	v_mul_f32_e32 v65, v181, v65
	v_mul_f32_e32 v66, v181, v66
	v_mul_f32_e32 v67, v181, v67
	v_mul_f32_e32 v68, v182, v68
	v_mul_f32_e32 v69, v182, v69
	v_mul_f32_e32 v70, v182, v70
	v_mul_f32_e32 v71, v182, v71
	v_mul_f32_e32 v72, v183, v72
	v_mul_f32_e32 v73, v183, v73
	v_mul_f32_e32 v74, v183, v74
	v_mul_f32_e32 v75, v183, v75
	v_cvt_pk_bf16_f32 v184, v44, v48
	v_cvt_pk_bf16_f32 v185, v52, v56
	v_cvt_pk_bf16_f32 v186, v60, v64
	v_cvt_pk_bf16_f32 v187, v68, v72
	global_store_dwordx4 v174, v[184:187], s[52:53]
	s_add_u32 s52, s52, 0x2000
	s_addc_u32 s53, s53, 0
	v_cvt_pk_bf16_f32 v188, v45, v49
	v_cvt_pk_bf16_f32 v189, v53, v57
	v_cvt_pk_bf16_f32 v190, v61, v65
	v_cvt_pk_bf16_f32 v191, v69, v73
	global_store_dwordx4 v174, v[188:191], s[52:53]
	s_add_u32 s52, s52, 0x2000
	s_addc_u32 s53, s53, 0
	v_cvt_pk_bf16_f32 v184, v46, v50
	v_cvt_pk_bf16_f32 v185, v54, v58
	v_cvt_pk_bf16_f32 v186, v62, v66
	v_cvt_pk_bf16_f32 v187, v70, v74
	global_store_dwordx4 v174, v[184:187], s[52:53]
	s_add_u32 s52, s52, 0x2000
	s_addc_u32 s53, s53, 0
	v_cvt_pk_bf16_f32 v188, v47, v51
	v_cvt_pk_bf16_f32 v189, v55, v59
	v_cvt_pk_bf16_f32 v190, v63, v67
	v_cvt_pk_bf16_f32 v191, v71, v75
	global_store_dwordx4 v174, v[188:191], s[52:53]
	s_add_u32 s52, s52, 0x3a000
	s_addc_u32 s53, s53, 0
	s_branch .Lcva_pd_0
.Lcva_pad_0:
	v_mov_b32_e32 v184, 0
	v_mov_b32_e32 v185, 0
	v_mov_b32_e32 v186, 0
	v_mov_b32_e32 v187, 0
	global_store_dwordx4 v174, v[184:187], s[52:53]
	s_add_u32 s52, s52, 0x2000
	s_addc_u32 s53, s53, 0
	global_store_dwordx4 v174, v[184:187], s[52:53]
	s_add_u32 s52, s52, 0x2000
	s_addc_u32 s53, s53, 0
	global_store_dwordx4 v174, v[184:187], s[52:53]
	s_add_u32 s52, s52, 0x2000
	s_addc_u32 s53, s53, 0
	global_store_dwordx4 v174, v[184:187], s[52:53]
	s_add_u32 s52, s52, 0x3a000
	s_addc_u32 s53, s53, 0
	s_nop 1
.Lcva_pd_0:
	s_bitcmp1_b32 s60, 0
	s_cbranch_scc0 .Lcva_ni_0
	s_lshl_b32 vcc_lo, s55, 2
	s_add_i32 vcc_lo, vcc_lo, s54
	s_add_i32 vcc_lo, vcc_lo, 0
	s_lshl_b32 vcc_hi, vcc_lo, 7
	s_cmp_eq_u32 s47, 0
	s_cbranch_scc1 .Lcva_col_l0
	s_cmp_lt_u32 vcc_lo, 0xe0
	s_cbranch_scc1 .Lcva_col_l0
	s_add_i32 vcc_hi, vcc_hi, 0x180
	s_cmp_lt_u32 vcc_lo, 0x160
	s_cbranch_scc1 .Lcva_col_l0
	s_sub_i32 vcc_hi, vcc_hi, 0x4180
	s_cmp_lt_u32 vcc_lo, 0x163
	s_cbranch_scc1 .Lcva_col_l0
	s_mov_b32 vcc_hi, 0
	s_or_b32 s59, s59, 16
.Lcva_col_l0:
	s_lshl_b32 vcc_lo, s61, 6
	s_mul_i32 vcc_lo, vcc_lo, s46
	s_add_u32 s62, s44, vcc_lo
	s_addc_u32 s63, s45, 0
	s_add_u32 s62, s62, vcc_hi
	s_addc_u32 s63, s63, 0
	global_load_dwordx4 v[44:47], v172, s[62:63] nt
	s_add_u32 s62, s62, s46
	s_addc_u32 s63, s63, 0
	global_load_dwordx4 v[48:51], v172, s[62:63] nt
	s_add_u32 s62, s62, s46
	s_addc_u32 s63, s63, 0
	global_load_dwordx4 v[52:55], v172, s[62:63] nt
	s_add_u32 s62, s62, s46
	s_addc_u32 s63, s63, 0
	global_load_dwordx4 v[56:59], v172, s[62:63] nt
	s_add_u32 s62, s62, s46
	s_addc_u32 s63, s63, 0
	global_load_dwordx4 v[60:63], v172, s[62:63] nt
	s_add_u32 s62, s62, s46
	s_addc_u32 s63, s63, 0
	global_load_dwordx4 v[64:67], v172, s[62:63] nt
	s_add_u32 s62, s62, s46
	s_addc_u32 s63, s63, 0
	global_load_dwordx4 v[68:71], v172, s[62:63] nt
	s_add_u32 s62, s62, s46
	s_addc_u32 s63, s63, 0
	global_load_dwordx4 v[72:75], v172, s[62:63] nt
.Lcva_ni_0:
	s_bitcmp1_b32 s60, 0
	s_cbranch_scc0 .Lcva_wl_1
	s_bitcmp1_b32 s60, 1
	s_cbranch_scc1 .Lcva_wf_1
	s_waitcnt vmcnt(36)
	s_branch .Lcva_wd_1
.Lcva_wf_1:
	s_waitcnt vmcnt(28)
	s_branch .Lcva_wd_1
.Lcva_wl_1:
	s_waitcnt vmcnt(20)
.Lcva_wd_1:
	s_bitcmp1_b32 s59, 1
	s_cbranch_scc1 .Lcva_pad_1
	v_mul_f32_e32 v76, v176, v76
	v_mul_f32_e32 v77, v176, v77
	v_mul_f32_e32 v78, v176, v78
	v_mul_f32_e32 v79, v176, v79
	v_mul_f32_e32 v80, v177, v80
	v_mul_f32_e32 v81, v177, v81
	v_mul_f32_e32 v82, v177, v82
	v_mul_f32_e32 v83, v177, v83
	v_mul_f32_e32 v84, v178, v84
	v_mul_f32_e32 v85, v178, v85
	v_mul_f32_e32 v86, v178, v86
	v_mul_f32_e32 v87, v178, v87
	v_mul_f32_e32 v88, v179, v88
	v_mul_f32_e32 v89, v179, v89
	v_mul_f32_e32 v90, v179, v90
	v_mul_f32_e32 v91, v179, v91
	v_mul_f32_e32 v92, v180, v92
	v_mul_f32_e32 v93, v180, v93
	v_mul_f32_e32 v94, v180, v94
	v_mul_f32_e32 v95, v180, v95
	v_mul_f32_e32 v96, v181, v96
	v_mul_f32_e32 v97, v181, v97
	v_mul_f32_e32 v98, v181, v98
	v_mul_f32_e32 v99, v181, v99
	v_mul_f32_e32 v100, v182, v100
	v_mul_f32_e32 v101, v182, v101
	v_mul_f32_e32 v102, v182, v102
	v_mul_f32_e32 v103, v182, v103
	v_mul_f32_e32 v104, v183, v104
	v_mul_f32_e32 v105, v183, v105
	v_mul_f32_e32 v106, v183, v106
	v_mul_f32_e32 v107, v183, v107
	v_cvt_pk_bf16_f32 v184, v76, v80
	v_cvt_pk_bf16_f32 v185, v84, v88
	v_cvt_pk_bf16_f32 v186, v92, v96
	v_cvt_pk_bf16_f32 v187, v100, v104
	global_store_dwordx4 v174, v[184:187], s[52:53]
	s_add_u32 s52, s52, 0x2000
	s_addc_u32 s53, s53, 0
	v_cvt_pk_bf16_f32 v188, v77, v81
	v_cvt_pk_bf16_f32 v189, v85, v89
	v_cvt_pk_bf16_f32 v190, v93, v97
	v_cvt_pk_bf16_f32 v191, v101, v105
	global_store_dwordx4 v174, v[188:191], s[52:53]
	s_add_u32 s52, s52, 0x2000
	s_addc_u32 s53, s53, 0
	v_cvt_pk_bf16_f32 v184, v78, v82
	v_cvt_pk_bf16_f32 v185, v86, v90
	v_cvt_pk_bf16_f32 v186, v94, v98
	v_cvt_pk_bf16_f32 v187, v102, v106
	global_store_dwordx4 v174, v[184:187], s[52:53]
	s_add_u32 s52, s52, 0x2000
	s_addc_u32 s53, s53, 0
	v_cvt_pk_bf16_f32 v188, v79, v83
	v_cvt_pk_bf16_f32 v189, v87, v91
	v_cvt_pk_bf16_f32 v190, v95, v99
	v_cvt_pk_bf16_f32 v191, v103, v107
	global_store_dwordx4 v174, v[188:191], s[52:53]
	s_add_u32 s52, s52, 0x3a000
	s_addc_u32 s53, s53, 0
	s_branch .Lcva_pd_1

; __device__ __forceinline__ void p0_transpose_item(const float* W, int K, int N, bf16* WT, int kb, int src_col0, int dst_row0, float* scr, int lane, const float* kgain = nullptr) {
;     ...
;         for (int i = 0; i < 32; ++i) { const int kk = 2 * i + (lane >> 5); wv[i] = __builtin_nontemporal_load(&W[(size_t)(k0 + kk) * N + src_col0 + (lane & 31)]); }
.Lcva_pd_1:
	s_bitcmp1_b32 s60, 0
	s_cbranch_scc0 .Lcva_ni_1
	s_lshl_b32 vcc_lo, s55, 2
	s_add_i32 vcc_lo, vcc_lo, s54
	s_add_i32 vcc_lo, vcc_lo, 1
	s_lshl_b32 vcc_hi, vcc_lo, 7
	s_cmp_eq_u32 s47, 0
	s_cbranch_scc1 .Lcva_col_l1
	s_cmp_lt_u32 vcc_lo, 0xe0
	s_cbranch_scc1 .Lcva_col_l1
	s_add_i32 vcc_hi, vcc_hi, 0x180
	s_cmp_lt_u32 vcc_lo, 0x160
	s_cbranch_scc1 .Lcva_col_l1
	s_sub_i32 vcc_hi, vcc_hi, 0x4180
	s_cmp_lt_u32 vcc_lo, 0x163
	s_cbranch_scc1 .Lcva_col_l1
	s_mov_b32 vcc_hi, 0
	s_or_b32 s59, s59, 32
.Lcva_col_l1:
	s_lshl_b32 vcc_lo, s61, 6
	s_mul_i32 vcc_lo, vcc_lo, s46
	s_add_u32 s62, s44, vcc_lo
	s_addc_u32 s63, s45, 0
	s_add_u32 s62, s62, vcc_hi
	s_addc_u32 s63, s63, 0
	global_load_dwordx4 v[76:79], v172, s[62:63] nt
	s_add_u32 s62, s62, s46
	s_addc_u32 s63, s63, 0
	global_load_dwordx4 v[80:83], v172, s[62:63] nt
	s_add_u32 s62, s62, s46
	s_addc_u32 s63, s63, 0
	global_load_dwordx4 v[84:87], v172, s[62:63] nt
	s_add_u32 s62, s62, s46
	s_addc_u32 s63, s63, 0
	global_load_dwordx4 v[88:91], v172, s[62:63] nt
	s_add_u32 s62, s62, s46
	s_addc_u32 s63, s63, 0
	global_load_dwordx4 v[92:95], v172, s[62:63] nt
	s_add_u32 s62, s62, s46
	s_addc_u32 s63, s63, 0
	global_load_dwordx4 v[96:99], v172, s[62:63] nt
	s_add_u32 s62, s62, s46
	s_addc_u32 s63, s63, 0
	global_load_dwordx4 v[100:103], v172, s[62:63] nt
	s_add_u32 s62, s62, s46
	s_addc_u32 s63, s63, 0
	global_load_dwordx4 v[104:107], v172, s[62:63] nt

; __device__ __forceinline__ unsigned pk2(float lo, float hi) { unsigned r; asm volatile("v_cvt_pk_bf16_f32 %0, %1, %2" : "=v"(r) : "v"(lo), "v"(hi)); return r; }
; __device__ __forceinline__ void p0_transpose_item(const float* W, int K, int N, bf16* WT, int kb, int src_col0, int dst_row0, float* scr, int lane, const float* kgain = nullptr) {
;     ...
;     __builtin_amdgcn_s_waitcnt(0xC07F); asm volatile("" ::: "memory");
; #pragma unroll
;     for (int j = 0; j < 4; ++j) { const int n = (lane >> 3) + 8 * j; const float* s = scr + (8 * c) * 33 + n;
;         v4u o;
;         if (src_col0 >= 0) { o.x = pk2(s[0 * 33] * g0.x, s[1 * 33] * g0.y); o.y = pk2(s[2 * 33] * g0.z, s[3 * 33] * g0.w); o.z = pk2(s[4 * 33] * g1.x, s[5 * 33] * g1.y); o.w = pk2(s[6 * 33] * g1.z, s[7 * 33] * g1.w); }
;         else { o.x = 0u; o.y = 0u; o.z = 0u; o.w = 0u; }
;         *(v4u*)(WT + (size_t)(dst_row0 + n) * K + k0 + 8 * c) = o; }
.Lcva_wf_2:
	s_waitcnt vmcnt(32)
	s_branch .Lcva_wd_2

; __device__ __forceinline__ unsigned pk2(float lo, float hi) { unsigned r; asm volatile("v_cvt_pk_bf16_f32 %0, %1, %2" : "=v"(r) : "v"(lo), "v"(hi)); return r; }
; __device__ __forceinline__ void p0_transpose_item(const float* W, int K, int N, bf16* WT, int kb, int src_col0, int dst_row0, float* scr, int lane, const float* kgain = nullptr) {
;     ...
;     for (int j = 0; j < 4; ++j) { const int n = (lane >> 3) + 8 * j; const float* s = scr + (8 * c) * 33 + n;
;         v4u o;
;         if (src_col0 >= 0) { o.x = pk2(s[0 * 33] * g0.x, s[1 * 33] * g0.y); o.y = pk2(s[2 * 33] * g0.z, s[3 * 33] * g0.w); o.z = pk2(s[4 * 33] * g1.x, s[5 * 33] * g1.y); o.w = pk2(s[6 * 33] * g1.z, s[7 * 33] * g1.w); }
;         else { o.x = 0u; o.y = 0u; o.z = 0u; o.w = 0u; }
;         *(v4u*)(WT + (size_t)(dst_row0 + n) * K + k0 + 8 * c) = o; }
.Lcva_wd_2:
	s_bitcmp1_b32 s59, 2
	s_cbranch_scc1 .Lcva_pad_2
	v_mul_f32_e32 v108, v176, v108
	v_mul_f32_e32 v109, v176, v109
	v_mul_f32_e32 v110, v176, v110
	v_mul_f32_e32 v111, v176, v111
	v_mul_f32_e32 v112, v177, v112
	v_mul_f32_e32 v113, v177, v113
	v_mul_f32_e32 v114, v177, v114
	v_mul_f32_e32 v115, v177, v115
	v_mul_f32_e32 v116, v178, v116
	v_mul_f32_e32 v117, v178, v117
	v_mul_f32_e32 v118, v178, v118
	v_mul_f32_e32 v119, v178, v119
	v_mul_f32_e32 v120, v179, v120
	v_mul_f32_e32 v121, v179, v121
	v_mul_f32_e32 v122, v179, v122
	v_mul_f32_e32 v123, v179, v123
	v_mul_f32_e32 v124, v180, v124
	v_mul_f32_e32 v125, v180, v125
	v_mul_f32_e32 v126, v180, v126
	v_mul_f32_e32 v127, v180, v127
	v_mul_f32_e32 v128, v181, v128
	v_mul_f32_e32 v129, v181, v129
	v_mul_f32_e32 v130, v181, v130
	v_mul_f32_e32 v131, v181, v131
	v_mul_f32_e32 v132, v182, v132
	v_mul_f32_e32 v133, v182, v133
	v_mul_f32_e32 v134, v182, v134
	v_mul_f32_e32 v135, v182, v135
	v_mul_f32_e32 v136, v183, v136
	v_mul_f32_e32 v137, v183, v137
	v_mul_f32_e32 v138, v183, v138
	v_mul_f32_e32 v139, v183, v139
	v_cvt_pk_bf16_f32 v184, v108, v112
	v_cvt_pk_bf16_f32 v185, v116, v120
	v_cvt_pk_bf16_f32 v186, v124, v128
	v_cvt_pk_bf16_f32 v187, v132, v136
	global_store_dwordx4 v174, v[184:187], s[52:53]
	s_add_u32 s52, s52, 0x2000
	s_addc_u32 s53, s53, 0
	v_cvt_pk_bf16_f32 v188, v109, v113
	v_cvt_pk_bf16_f32 v189, v117, v121
	v_cvt_pk_bf16_f32 v190, v125, v129
	v_cvt_pk_bf16_f32 v191, v133, v137
	global_store_dwordx4 v174, v[188:191], s[52:53]
	s_add_u32 s52, s52, 0x2000
	s_addc_u32 s53, s53, 0
	v_cvt_pk_bf16_f32 v184, v110, v114
	v_cvt_pk_bf16_f32 v185, v118, v122
	v_cvt_pk_bf16_f32 v186, v126, v130
	v_cvt_pk_bf16_f32 v187, v134, v138
	global_store_dwordx4 v174, v[184:187], s[52:53]
	s_add_u32 s52, s52, 0x2000
	s_addc_u32 s53, s53, 0
	v_cvt_pk_bf16_f32 v188, v111, v115
	v_cvt_pk_bf16_f32 v189, v119, v123
	v_cvt_pk_bf16_f32 v190, v127, v131
	v_cvt_pk_bf16_f32 v191, v135, v139
	global_store_dwordx4 v174, v[188:191], s[52:53]
	s_add_u32 s52, s52, 0x3a000
	s_addc_u32 s53, s53, 0
	s_branch .Lcva_pd_2

; template <class CM, class RM>
; __device__ __forceinline__ void p0_transpose_matrix2(Frame& F, const float* W, int K, int N, bf16* WT, int nblk, CM colmap, RM rowmap, int& it0, const float* kgain = nullptr) {
;     float* scr = (float*)(F.lds + RING_OFF + F.wave * 16384);
;     const int nitems = (K / 64) * nblk;
;     int first = (F.gw - (it0 % F.ngw) + F.ngw) % F.ngw;
;     for (int r = first; r < nitems; r += F.ngw) {
;         const int kb = r / nblk, nb = r % nblk;
;         p0_transpose_item(W, K, N, WT, kb, colmap(nb), rowmap(nb), scr, F.lane, kgain);
;     }
.Lcva_pd_2:
	s_bitcmp1_b32 s60, 0
	s_cbranch_scc0 .Lcva_ni_2
	s_lshl_b32 vcc_lo, s55, 2
	s_add_i32 vcc_lo, vcc_lo, s54
	s_add_i32 vcc_lo, vcc_lo, 2
	s_lshl_b32 vcc_hi, vcc_lo, 7
	s_cmp_eq_u32 s47, 0
	s_cbranch_scc1 .Lcva_col_l2
	s_cmp_lt_u32 vcc_lo, 0xe0
	s_cbranch_scc1 .Lcva_col_l2
	s_add_i32 vcc_hi, vcc_hi, 0x180
	s_cmp_lt_u32 vcc_lo, 0x160
	s_cbranch_scc1 .Lcva_col_l2
	s_sub_i32 vcc_hi, vcc_hi, 0x4180
	s_cmp_lt_u32 vcc_lo, 0x163
	s_cbranch_scc1 .Lcva_col_l2
	s_mov_b32 vcc_hi, 0
	s_or_b32 s59, s59, 64
.Lcva_col_l2:
	s_lshl_b32 vcc_lo, s61, 6
	s_mul_i32 vcc_lo, vcc_lo, s46
	s_add_u32 s62, s44, vcc_lo
	s_addc_u32 s63, s45, 0
	s_add_u32 s62, s62, vcc_hi
	s_addc_u32 s63, s63, 0
	global_load_dwordx4 v[108:111], v172, s[62:63] nt
	s_add_u32 s62, s62, s46
	s_addc_u32 s63, s63, 0
	global_load_dwordx4 v[112:115], v172, s[62:63] nt
	s_add_u32 s62, s62, s46
	s_addc_u32 s63, s63, 0
	global_load_dwordx4 v[116:119], v172, s[62:63] nt
	s_add_u32 s62, s62, s46
	s_addc_u32 s63, s63, 0
	global_load_dwordx4 v[120:123], v172, s[62:63] nt
	s_add_u32 s62, s62, s46
	s_addc_u32 s63, s63, 0
	global_load_dwordx4 v[124:127], v172, s[62:63] nt
	s_add_u32 s62, s62, s46
	s_addc_u32 s63, s63, 0
	global_load_dwordx4 v[128:131], v172, s[62:63] nt
	s_add_u32 s62, s62, s46
	s_addc_u32 s63, s63, 0
	global_load_dwordx4 v[132:135], v172, s[62:63] nt
	s_add_u32 s62, s62, s46
	s_addc_u32 s63, s63, 0
	global_load_dwordx4 v[136:139], v172, s[62:63] nt

; __device__ __forceinline__ unsigned pk2(float lo, float hi) { unsigned r; asm volatile("v_cvt_pk_bf16_f32 %0, %1, %2" : "=v"(r) : "v"(lo), "v"(hi)); return r; }
; __device__ __forceinline__ void p0_transpose_item(const float* W, int K, int N, bf16* WT, int kb, int src_col0, int dst_row0, float* scr, int lane, const float* kgain = nullptr) {
;     ...
;     for (int j = 0; j < 4; ++j) { const int n = (lane >> 3) + 8 * j; const float* s = scr + (8 * c) * 33 + n;
;         v4u o;
;         if (src_col0 >= 0) { o.x = pk2(s[0 * 33] * g0.x, s[1 * 33] * g0.y); o.y = pk2(s[2 * 33] * g0.z, s[3 * 33] * g0.w); o.z = pk2(s[4 * 33] * g1.x, s[5 * 33] * g1.y); o.w = pk2(s[6 * 33] * g1.z, s[7 * 33] * g1.w); }
;         else { o.x = 0u; o.y = 0u; o.z = 0u; o.w = 0u; }
;         *(v4u*)(WT + (size_t)(dst_row0 + n) * K + k0 + 8 * c) = o; }
.Lcva_wf_3:
	s_waitcnt vmcnt(36)
	s_branch .Lcva_wd_3
.Lcva_wl_3:
	s_waitcnt vmcnt(12)
.Lcva_wd_3:
	s_bitcmp1_b32 s59, 3
	s_cbranch_scc1 .Lcva_pad_3
	v_mul_f32_e32 v140, v176, v140
	v_mul_f32_e32 v141, v176, v141
	v_mul_f32_e32 v142, v176, v142
	v_mul_f32_e32 v143, v176, v143
	v_mul_f32_e32 v144, v177, v144
	v_mul_f32_e32 v145, v177, v145
	v_mul_f32_e32 v146, v177, v146
	v_mul_f32_e32 v147, v177, v147
	v_mul_f32_e32 v148, v178, v148
	v_mul_f32_e32 v149, v178, v149
	v_mul_f32_e32 v150, v178, v150
	v_mul_f32_e32 v151, v178, v151
	v_mul_f32_e32 v152, v179, v152
	v_mul_f32_e32 v153, v179, v153
	v_mul_f32_e32 v154, v179, v154
	v_mul_f32_e32 v155, v179, v155
	v_mul_f32_e32 v156, v180, v156
	v_mul_f32_e32 v157, v180, v157
	v_mul_f32_e32 v158, v180, v158
	v_mul_f32_e32 v159, v180, v159
	v_mul_f32_e32 v160, v181, v160
	v_mul_f32_e32 v161, v181, v161
	v_mul_f32_e32 v162, v181, v162
	v_mul_f32_e32 v163, v181, v163
	v_mul_f32_e32 v164, v182, v164
	v_mul_f32_e32 v165, v182, v165
	v_mul_f32_e32 v166, v182, v166
	v_mul_f32_e32 v167, v182, v167
	v_mul_f32_e32 v168, v183, v168
	v_mul_f32_e32 v169, v183, v169
	v_mul_f32_e32 v170, v183, v170
	v_mul_f32_e32 v171, v183, v171
	v_cvt_pk_bf16_f32 v184, v140, v144
	v_cvt_pk_bf16_f32 v185, v148, v152
	v_cvt_pk_bf16_f32 v186, v156, v160
	v_cvt_pk_bf16_f32 v187, v164, v168
	global_store_dwordx4 v174, v[184:187], s[52:53]
	s_add_u32 s52, s52, 0x2000
	s_addc_u32 s53, s53, 0
	v_cvt_pk_bf16_f32 v188, v141, v145
	v_cvt_pk_bf16_f32 v189, v149, v153
	v_cvt_pk_bf16_f32 v190, v157, v161
	v_cvt_pk_bf16_f32 v191, v165, v169
	global_store_dwordx4 v174, v[188:191], s[52:53]
	s_add_u32 s52, s52, 0x2000
	s_addc_u32 s53, s53, 0
	v_cvt_pk_bf16_f32 v184, v142, v146
	v_cvt_pk_bf16_f32 v185, v150, v154
	v_cvt_pk_bf16_f32 v186, v158, v162
	v_cvt_pk_bf16_f32 v187, v166, v170
	global_store_dwordx4 v174, v[184:187], s[52:53]
	s_add_u32 s52, s52, 0x2000
	s_addc_u32 s53, s53, 0
	v_cvt_pk_bf16_f32 v188, v143, v147
	v_cvt_pk_bf16_f32 v189, v151, v155
	v_cvt_pk_bf16_f32 v190, v159, v163
	v_cvt_pk_bf16_f32 v191, v167, v171
	global_store_dwordx4 v174, v[188:191], s[52:53]
	s_add_u32 s52, s52, 0x3a000
	s_addc_u32 s53, s53, 0
	s_branch .Lcva_pd_3

; template <class CM, class RM>
; __device__ __forceinline__ void p0_transpose_matrix2(Frame& F, const float* W, int K, int N, bf16* WT, int nblk, CM colmap, RM rowmap, int& it0, const float* kgain = nullptr) {
;     float* scr = (float*)(F.lds + RING_OFF + F.wave * 16384);
;     const int nitems = (K / 64) * nblk;
;     int first = (F.gw - (it0 % F.ngw) + F.ngw) % F.ngw;
;     for (int r = first; r < nitems; r += F.ngw) {
;         const int kb = r / nblk, nb = r % nblk;
;         p0_transpose_item(W, K, N, WT, kb, colmap(nb), rowmap(nb), scr, F.lane, kgain);
;     }
.Lcva_pd_3:
	s_bitcmp1_b32 s60, 0
	s_cbranch_scc0 .Lcva_ni_3
	s_lshl_b32 vcc_lo, s55, 2
	s_add_i32 vcc_lo, vcc_lo, s54
	s_add_i32 vcc_lo, vcc_lo, 3
	s_lshl_b32 vcc_hi, vcc_lo, 7
	s_cmp_eq_u32 s47, 0
	s_cbranch_scc1 .Lcva_col_l3
	s_cmp_lt_u32 vcc_lo, 0xe0
	s_cbranch_scc1 .Lcva_col_l3
	s_add_i32 vcc_hi, vcc_hi, 0x180
	s_cmp_lt_u32 vcc_lo, 0x160
	s_cbranch_scc1 .Lcva_col_l3
	s_sub_i32 vcc_hi, vcc_hi, 0x4180
	s_cmp_lt_u32 vcc_lo, 0x163
	s_cbranch_scc1 .Lcva_col_l3
	s_mov_b32 vcc_hi, 0
	s_or_b32 s59, s59, 128

; template <class CM, class RM>
; __device__ __forceinline__ void p0_transpose_matrix2(Frame& F, const float* W, int K, int N, bf16* WT, int nblk, CM colmap, RM rowmap, int& it0, const float* kgain = nullptr) {
;     ...
;     for (int r = first; r < nitems; r += F.ngw) {
;         const int kb = r / nblk, nb = r % nblk;
;         p0_transpose_item(W, K, N, WT, kb, colmap(nb), rowmap(nb), scr, F.lane, kgain);
;     }
;     it0 += nitems;
.Lcva_ni_3:
	s_andn2_b32 s60, s60, 2
	s_bitcmp1_b32 s60, 0
	s_cbranch_scc1 .Lcva_loop
.Lcva_exit:
	s_waitcnt vmcnt(0)
	s_cmp_eq_u32 s32, 0
	s_cbranch_scc1 .Lcv_ret0
	s_cmp_eq_u32 s32, 1
	s_cbranch_scc1 .Lcv_ret1
	s_cmp_eq_u32 s32, 2
	s_cbranch_scc1 .Lcv_ret2
	s_cmp_eq_u32 s32, 3
	s_cbranch_scc1 .Lcv_ret3
	s_branch .Lcv_ret4
